# v_c15 + softmax row-sum init folded: ps = 0 + p0; ps += p1 -> ps = p1 + p0 (two sites, exact)
# baseline (speedup 1.0000x reference)
; __device__ __forceinline__ unsigned pk2(float lo, float hi) { const f32x2 v = {lo, hi}; const bf16x2_n b = __builtin_convertvector(v, bf16x2_n); return __builtin_bit_cast(unsigned, b); }
; #define ATT_PV(src_, mt_) do { _Pragma("unroll") for (int e = 0; e < 2; ++e) O[mt_] = mfma16(src_[e], pf[e], O[mt_]); } while (0)
; #define ATT_SB() __builtin_amdgcn_sched_barrier(0)
; __device__ __forceinline__ void attn_phase(LAS unsigned char* lds, const bf16* PROJ, bf16* MIX, const float* lq1, const float* lk1, const float* lq2, const float* lk2,
;                                            const float* norm_g, float lambda_init, int G, int wave_s) {
;     ...
;                 float ps = 0.f;
; #pragma unroll
;                 for (int t16 = 0; t16 < 4; ++t16)
; #pragma unroll
;                     for (int r = 0; r < 4; ++r) { const float pv = __builtin_amdgcn_exp2f(s[t16][r] - mn); s[t16][r] = pv; ps += pv; }
;                 l_part = l_part * alpha + ps;
;                 bf16x8 pf[2];
; #pragma unroll
;                 for (int ks = 0; ks < 2; ++ks) { v4u pw; pw.x = pk2(s[2 * ks][0], s[2 * ks][1]); pw.y = pk2(s[2 * ks][2], s[2 * ks][3]); pw.z = pk2(s[2 * ks + 1][0], s[2 * ks + 1][1]); pw.w = pk2(s[2 * ks + 1][2], s[2 * ks + 1][3]);
;                     pf[ks] = __builtin_bit_cast(bf16x8, pw); }
;                 { bf16x8 va[2], vb[2], vc[2];
;                   ATT_LDV(va, 0); ATT_LDV(vb, 1);
;                   if (resc) {
; #pragma unroll
;                   for (int mt = 0; mt < 16; ++mt) O[mt] = O[mt] * alpha; }
;                   ATT_SB();
;                   ATT_LDV(vc, 2); ATT_PV(va, 0); ATT_SB(); ATT_LDV(va, 3); ATT_PV(vb, 1); ATT_SB(); ATT_LDV(vb, 4); ATT_PV(vc, 2); ATT_SB(); ATT_LDV(vc, 5); ATT_PV(va, 3); ATT_SB();
;                   ATT_LDV(va, 6); ATT_PV(vb, 4); ATT_SB(); ATT_LDV(vb, 7); ATT_PV(vc, 5); ATT_SB(); ATT_LDV(vc, 8); ATT_PV(va, 6); ATT_SB(); ATT_LDV(va, 9); ATT_PV(vb, 7); ATT_SB();
;                   ATT_LDV(vb, 10); ATT_PV(vc, 8); ATT_SB(); ATT_LDV(vc, 11); ATT_PV(va, 9); ATT_SB(); ATT_LDV(va, 12); ATT_PV(vb, 10); ATT_SB(); ATT_LDV(vb, 13); ATT_PV(vc, 11); ATT_SB();
;                   ATT_LDV(vc, 14); ATT_PV(va, 12); ATT_SB(); ATT_LDV(va, 15); ATT_PV(vb, 13); ATT_SB(); ATT_PV(vc, 14); ATT_SB(); ATT_PV(va, 15); ATT_SB();
.LBB0_894:
	v_sub_f32_e32 v130, v130, v228
	v_exp_f32_e32 v130, v130
	v_sub_f32_e32 v131, v131, v228
	v_exp_f32_e32 v131, v131
	v_sub_f32_e32 v132, v132, v228
	v_exp_f32_e32 v132, v132
	v_sub_f32_e32 v133, v133, v228
	v_exp_f32_e32 v133, v133
	v_sub_f32_e32 v134, v134, v228
	v_exp_f32_e32 v134, v134
	v_sub_f32_e32 v135, v135, v228
	v_add_f32_e32 v212, v131, v130
	v_exp_f32_e32 v135, v135
	v_sub_f32_e32 v136, v136, v228
	v_add_f32_e32 v212, v132, v212
	v_exp_f32_e32 v136, v136
	v_sub_f32_e32 v137, v137, v228
	v_add_f32_e32 v212, v133, v212
	v_exp_f32_e32 v137, v137
	v_sub_f32_e32 v213, v227, v228
	v_add_f32_e32 v212, v134, v212
	v_exp_f32_e32 v213, v213
	v_sub_f32_e32 v226, v229, v228
	v_add_f32_e32 v212, v135, v212
	v_exp_f32_e32 v226, v226
	v_sub_f32_e32 v227, v230, v228
	v_add_f32_e32 v212, v136, v212
	v_exp_f32_e32 v227, v227
	v_sub_f32_e32 v229, v231, v228
	v_add_f32_e32 v212, v137, v212
	v_exp_f32_e32 v229, v229
	v_sub_f32_e32 v230, v232, v228
	v_add_f32_e32 v212, v213, v212
	v_exp_f32_e32 v230, v230
	v_sub_f32_e32 v231, v233, v228
	v_add_f32_e32 v212, v226, v212
	v_exp_f32_e32 v231, v231
	v_sub_f32_e32 v232, v234, v228
	v_add_f32_e32 v212, v227, v212
	v_exp_f32_e32 v232, v232
	v_sub_f32_e32 v233, v235, v228
	v_add_f32_e32 v212, v229, v212
	v_exp_f32_e32 v233, v233
	v_add_f32_e32 v212, v230, v212
	v_add_f32_e32 v212, v231, v212
	v_add_f32_e32 v212, v232, v212
	v_cvt_pk_bf16_f32 v130, v130, v131
	v_cvt_pk_bf16_f32 v131, v132, v133
	v_cvt_pk_bf16_f32 v132, v134, v135
	v_cvt_pk_bf16_f32 v135, v227, v229
	v_add_f32_e32 v227, v233, v212
	v_fmac_f32_e32 v227, v225, v0
	v_cvt_pk_bf16_f32 v133, v136, v137
	v_cvt_pk_bf16_f32 v134, v213, v226
	v_cvt_pk_bf16_f32 v136, v230, v231
	v_cvt_pk_bf16_f32 v137, v232, v233
	s_waitcnt lgkmcnt(5)
	v_mfma_f32_16x16x32_bf16 v[62:65], v[126:129], v[130:133], v[62:65]
	ds_read_b64_tr_b16 v[126:127], v162 offset:34880
	ds_read_b64_tr_b16 v[128:129], v162 offset:43584
	ds_read_b64_tr_b16 v[230:231], v162 offset:52288
	ds_read_b64_tr_b16 v[232:233], v162 offset:60992
	s_waitcnt lgkmcnt(7)
	v_mfma_f32_16x16x32_bf16 v[62:65], v[122:125], v[134:137], v[62:65]
	s_waitcnt lgkmcnt(6)
	v_mfma_f32_16x16x32_bf16 v[58:61], v[114:117], v[130:133], v[58:61]
	ds_read_b64_tr_b16 v[114:115], v162 offset:34912
	ds_read_b64_tr_b16 v[116:117], v162 offset:43616
	ds_read_b64_tr_b16 v[122:123], v162 offset:52320
	ds_read_b64_tr_b16 v[124:125], v162 offset:61024
	s_waitcnt lgkmcnt(8)
	v_mfma_f32_16x16x32_bf16 v[58:61], v[118:121], v[134:137], v[58:61]
	s_waitcnt lgkmcnt(6)
	v_mfma_f32_16x16x32_bf16 v[54:57], v[126:129], v[130:133], v[54:57]
	ds_read_b64_tr_b16 v[118:119], v162 offset:34944
	ds_read_b64_tr_b16 v[120:121], v162 offset:43648
	ds_read_b64_tr_b16 v[126:127], v162 offset:52352
	ds_read_b64_tr_b16 v[128:129], v162 offset:61056
	s_waitcnt lgkmcnt(8)
	v_mfma_f32_16x16x32_bf16 v[54:57], v[230:233], v[134:137], v[54:57]
	s_waitcnt lgkmcnt(6)
	v_mfma_f32_16x16x32_bf16 v[50:53], v[114:117], v[130:133], v[50:53]
	ds_read_b64_tr_b16 v[114:115], v162 offset:34976
	ds_read_b64_tr_b16 v[116:117], v162 offset:43680
	ds_read_b64_tr_b16 v[230:231], v162 offset:52384
	ds_read_b64_tr_b16 v[232:233], v162 offset:61088
	s_waitcnt lgkmcnt(8)
	v_mfma_f32_16x16x32_bf16 v[50:53], v[122:125], v[134:137], v[50:53]
	s_waitcnt lgkmcnt(6)
	v_mfma_f32_16x16x32_bf16 v[46:49], v[118:121], v[130:133], v[46:49]
	ds_read_b64_tr_b16 v[118:119], v162 offset:35008
	ds_read_b64_tr_b16 v[120:121], v162 offset:43712
	ds_read_b64_tr_b16 v[122:123], v162 offset:52416
	ds_read_b64_tr_b16 v[124:125], v162 offset:61120
	s_waitcnt lgkmcnt(8)
	v_mfma_f32_16x16x32_bf16 v[46:49], v[126:129], v[134:137], v[46:49]
	s_waitcnt lgkmcnt(6)
	v_mfma_f32_16x16x32_bf16 v[42:45], v[114:117], v[130:133], v[42:45]
	ds_read_b64_tr_b16 v[114:115], v162 offset:35040
	ds_read_b64_tr_b16 v[116:117], v162 offset:43744
	ds_read_b64_tr_b16 v[126:127], v162 offset:52448
	ds_read_b64_tr_b16 v[128:129], v162 offset:61152
	s_waitcnt lgkmcnt(8)
	v_mfma_f32_16x16x32_bf16 v[42:45], v[230:233], v[134:137], v[42:45]
	s_waitcnt lgkmcnt(6)
	v_mfma_f32_16x16x32_bf16 v[38:41], v[118:121], v[130:133], v[38:41]
	ds_read_b64_tr_b16 v[118:119], v162 offset:35072
	ds_read_b64_tr_b16 v[120:121], v162 offset:43776
	ds_read_b64_tr_b16 v[230:231], v162 offset:52480
	ds_read_b64_tr_b16 v[232:233], v162 offset:61184
	s_waitcnt lgkmcnt(8)
	v_mfma_f32_16x16x32_bf16 v[38:41], v[122:125], v[134:137], v[38:41]
	s_waitcnt lgkmcnt(6)
; #define ATT_LDV(dst_, mt_) do { _Pragma("unroll") for (int e = 0; e < 2; ++e) { const LAS unsigned char* vp = vb_ + e * 17408 + (mt_) * 32; \
;                     const s16x4 a0 = ds_tr16(vp), a1 = ds_tr16(vp + 8704); dst_[e] = (bf16x8){a0[0], a0[1], a0[2], a0[3], a1[0], a1[1], a1[2], a1[3]}; } } while (0)
; #define ATT_PV(src_, mt_) do { _Pragma("unroll") for (int e = 0; e < 2; ++e) O[mt_] = mfma16(src_[e], pf[e], O[mt_]); } while (0)
; #define ATT_SB() __builtin_amdgcn_sched_barrier(0)
; __device__ __forceinline__ void attn_phase(LAS unsigned char* lds, const bf16* PROJ, bf16* MIX, const float* lq1, const float* lk1, const float* lq2, const float* lk2,
;                                            const float* norm_g, float lambda_init, int G, int wave_s) {
;     ...
;                   ATT_LDV(vc, 2); ATT_PV(va, 0); ATT_SB(); ATT_LDV(va, 3); ATT_PV(vb, 1); ATT_SB(); ATT_LDV(vb, 4); ATT_PV(vc, 2); ATT_SB(); ATT_LDV(vc, 5); ATT_PV(va, 3); ATT_SB();
;                   ATT_LDV(va, 6); ATT_PV(vb, 4); ATT_SB(); ATT_LDV(vb, 7); ATT_PV(vc, 5); ATT_SB(); ATT_LDV(vc, 8); ATT_PV(va, 6); ATT_SB(); ATT_LDV(va, 9); ATT_PV(vb, 7); ATT_SB();
;                   ATT_LDV(vb, 10); ATT_PV(vc, 8); ATT_SB(); ATT_LDV(vc, 11); ATT_PV(va, 9); ATT_SB(); ATT_LDV(va, 12); ATT_PV(vb, 10); ATT_SB(); ATT_LDV(vb, 13); ATT_PV(vc, 11); ATT_SB();
;                   ATT_LDV(vc, 14); ATT_PV(va, 12); ATT_SB(); ATT_LDV(va, 15); ATT_PV(vb, 13); ATT_SB(); ATT_PV(vc, 14); ATT_SB(); ATT_PV(va, 15); ATT_SB();
;                   }
;                 __syncthreads();
;               }
;               if (kt0 + 1 <= qb) { const int kt = kt0 + 1;
;                 if (kt < qb) { ATT_WRITE(0); if (kt + 1 < qb) ATT_LOAD(qb - (kt + 2)); }
	v_mfma_f32_16x16x32_bf16 v[34:37], v[114:117], v[130:133], v[34:37]
	ds_read_b64_tr_b16 v[114:115], v162 offset:35104
	ds_read_b64_tr_b16 v[116:117], v162 offset:43808
	ds_read_b64_tr_b16 v[122:123], v162 offset:52512
	ds_read_b64_tr_b16 v[124:125], v162 offset:61216
	s_waitcnt lgkmcnt(8)
	v_mfma_f32_16x16x32_bf16 v[34:37], v[126:129], v[134:137], v[34:37]
	s_waitcnt lgkmcnt(6)
	v_mfma_f32_16x16x32_bf16 v[30:33], v[118:121], v[130:133], v[30:33]
	ds_read_b64_tr_b16 v[118:119], v162 offset:35136
	ds_read_b64_tr_b16 v[120:121], v162 offset:43840
	ds_read_b64_tr_b16 v[126:127], v162 offset:52544
	ds_read_b64_tr_b16 v[128:129], v162 offset:61248
	s_waitcnt lgkmcnt(8)
	v_mfma_f32_16x16x32_bf16 v[30:33], v[230:233], v[134:137], v[30:33]
	s_waitcnt lgkmcnt(6)
	v_mfma_f32_16x16x32_bf16 v[26:29], v[114:117], v[130:133], v[26:29]
	ds_read_b64_tr_b16 v[114:115], v162 offset:35168
	ds_read_b64_tr_b16 v[116:117], v162 offset:43872
	ds_read_b64_tr_b16 v[230:231], v162 offset:52576
	ds_read_b64_tr_b16 v[232:233], v162 offset:61280
	s_waitcnt lgkmcnt(8)
	v_mfma_f32_16x16x32_bf16 v[26:29], v[122:125], v[134:137], v[26:29]
	s_waitcnt lgkmcnt(6)
	v_mfma_f32_16x16x32_bf16 v[22:25], v[118:121], v[130:133], v[22:25]
	ds_read_b64_tr_b16 v[118:119], v162 offset:35200
	ds_read_b64_tr_b16 v[120:121], v162 offset:43904
	ds_read_b64_tr_b16 v[122:123], v162 offset:52608
	ds_read_b64_tr_b16 v[124:125], v162 offset:61312
	s_waitcnt lgkmcnt(8)
	v_mfma_f32_16x16x32_bf16 v[22:25], v[126:129], v[134:137], v[22:25]
	s_waitcnt lgkmcnt(6)
	v_mfma_f32_16x16x32_bf16 v[14:17], v[114:117], v[130:133], v[14:17]
	ds_read_b64_tr_b16 v[114:115], v162 offset:35232
	ds_read_b64_tr_b16 v[116:117], v162 offset:43936
	ds_read_b64_tr_b16 v[126:127], v162 offset:52640
	ds_read_b64_tr_b16 v[128:129], v162 offset:61344
	s_waitcnt lgkmcnt(8)
	v_mfma_f32_16x16x32_bf16 v[14:17], v[230:233], v[134:137], v[14:17]
	s_waitcnt lgkmcnt(6)
	v_mfma_f32_16x16x32_bf16 v[18:21], v[118:121], v[130:133], v[18:21]
	ds_read_b64_tr_b16 v[118:119], v162 offset:35264
	ds_read_b64_tr_b16 v[120:121], v162 offset:43968
	ds_read_b64_tr_b16 v[230:231], v162 offset:52672
	ds_read_b64_tr_b16 v[232:233], v162 offset:61376
	s_waitcnt lgkmcnt(8)
	v_mfma_f32_16x16x32_bf16 v[18:21], v[122:125], v[134:137], v[18:21]
	s_waitcnt lgkmcnt(6)
	v_mfma_f32_16x16x32_bf16 v[10:13], v[114:117], v[130:133], v[10:13]
	ds_read_b64_tr_b16 v[114:115], v162 offset:35296
	ds_read_b64_tr_b16 v[116:117], v162 offset:44000
	ds_read_b64_tr_b16 v[122:123], v162 offset:52704
	ds_read_b64_tr_b16 v[124:125], v162 offset:61408
	s_waitcnt lgkmcnt(8)
	v_mfma_f32_16x16x32_bf16 v[10:13], v[126:129], v[134:137], v[10:13]
	s_waitcnt lgkmcnt(6)
	v_mfma_f32_16x16x32_bf16 v[6:9], v[118:121], v[130:133], v[6:9]
	s_waitcnt lgkmcnt(4)
	v_mfma_f32_16x16x32_bf16 v[6:9], v[230:233], v[134:137], v[6:9]
	s_waitcnt lgkmcnt(2)
	v_mfma_f32_16x16x32_bf16 v[2:5], v[114:117], v[130:133], v[2:5]
	s_waitcnt lgkmcnt(0)
	v_mfma_f32_16x16x32_bf16 v[2:5], v[122:125], v[134:137], v[2:5]
	s_andn2_b64 vcc, exec, s[8:9]
	s_barrier
	s_cbranch_vccnz .LBB0_887
	s_add_i32 s8, s88, 1
	s_cmp_ge_u32 s8, s86
	s_cbranch_scc1 .LBB0_898
	s_cmp_ge_u32 s88, s87
	s_waitcnt vmcnt(7)
	ds_write_b128 v159, v[82:85]
	s_waitcnt vmcnt(6)
	ds_write_b128 v159, v[86:89] offset:17408
	s_waitcnt vmcnt(5)
	ds_write_b128 v215, v[90:93]
	s_waitcnt vmcnt(4)
	ds_write_b128 v215, v[94:97] offset:17408
	s_waitcnt vmcnt(3)
	ds_write_b128 v220, v[98:101] offset:34816
	s_waitcnt vmcnt(2)
	ds_write_b128 v221, v[102:105] offset:34816
	s_waitcnt vmcnt(1)
	ds_write_b128 v222, v[106:109] offset:34816
	s_waitcnt vmcnt(0)
	ds_write_b128 v223, v[110:113] offset:34816
	s_cbranch_scc1 .LBB0_898
	s_mov_b64 s[8:9], s[0:1]
	s_nop 0
	v_lshl_add_u64 v[86:87], s[8:9], 0, v[148:149]
	v_lshl_add_u64 v[94:95], s[8:9], 0, v[146:147]
	v_lshl_add_u64 v[98:99], s[8:9], 0, v[144:145]
	v_lshl_add_u64 v[102:103], s[8:9], 0, v[142:143]
	v_lshl_add_u64 v[106:107], s[8:9], 0, v[140:141]
	v_lshl_add_u64 v[110:111], s[8:9], 0, v[138:139]
	global_load_dwordx4 v[82:85], v[86:87], off
	s_nop 0
	global_load_dwordx4 v[86:89], v[86:87], off offset:256
	s_nop 0
	global_load_dwordx4 v[90:93], v[94:95], off
	s_nop 0
	global_load_dwordx4 v[94:97], v[94:95], off offset:256
	s_nop 0
	global_load_dwordx4 v[98:101], v[98:99], off
	s_nop 0
	global_load_dwordx4 v[102:105], v[102:103], off
	s_nop 0
	global_load_dwordx4 v[106:109], v[106:107], off
	s_nop 0
	global_load_dwordx4 v[110:113], v[110:111], off

; __device__ __forceinline__ unsigned pk2(float lo, float hi) { const f32x2 v = {lo, hi}; const bf16x2_n b = __builtin_convertvector(v, bf16x2_n); return __builtin_bit_cast(unsigned, b); }
; #define ATT_PV(src_, mt_) do { _Pragma("unroll") for (int e = 0; e < 2; ++e) O[mt_] = mfma16(src_[e], pf[e], O[mt_]); } while (0)
; #define ATT_SB() __builtin_amdgcn_sched_barrier(0)
; __device__ __forceinline__ void attn_phase(LAS unsigned char* lds, const bf16* PROJ, bf16* MIX, const float* lq1, const float* lk1, const float* lq2, const float* lk2,
;                                            const float* norm_g, float lambda_init, int G, int wave_s) {
;     ...
;                 float ps = 0.f;
; #pragma unroll
;                 for (int t16 = 0; t16 < 4; ++t16)
; #pragma unroll
;                     for (int r = 0; r < 4; ++r) { const float pv = __builtin_amdgcn_exp2f(s[t16][r] - mn); s[t16][r] = pv; ps += pv; }
;                 l_part = l_part * alpha + ps;
;                 bf16x8 pf[2];
; #pragma unroll
;                 for (int ks = 0; ks < 2; ++ks) { v4u pw; pw.x = pk2(s[2 * ks][0], s[2 * ks][1]); pw.y = pk2(s[2 * ks][2], s[2 * ks][3]); pw.z = pk2(s[2 * ks + 1][0], s[2 * ks + 1][1]); pw.w = pk2(s[2 * ks + 1][2], s[2 * ks + 1][3]);
;                     pf[ks] = __builtin_bit_cast(bf16x8, pw); }
;                 { bf16x8 va[2], vb[2], vc[2];
;                   ATT_LDV(va, 0); ATT_LDV(vb, 1);
;                   if (resc) {
; #pragma unroll
;                   for (int mt = 0; mt < 16; ++mt) O[mt] = O[mt] * alpha; }
;                   ATT_SB();
;                   ATT_LDV(vc, 2); ATT_PV(va, 0); ATT_SB(); ATT_LDV(va, 3); ATT_PV(vb, 1); ATT_SB(); ATT_LDV(vb, 4); ATT_PV(vc, 2); ATT_SB(); ATT_LDV(vc, 5); ATT_PV(va, 3); ATT_SB();
;                   ATT_LDV(va, 6); ATT_PV(vb, 4); ATT_SB(); ATT_LDV(vb, 7); ATT_PV(vc, 5); ATT_SB(); ATT_LDV(vc, 8); ATT_PV(va, 6); ATT_SB(); ATT_LDV(va, 9); ATT_PV(vb, 7); ATT_SB();
;                   ATT_LDV(vb, 10); ATT_PV(vc, 8); ATT_SB(); ATT_LDV(vc, 11); ATT_PV(va, 9); ATT_SB(); ATT_LDV(va, 12); ATT_PV(vb, 10); ATT_SB(); ATT_LDV(vb, 13); ATT_PV(vc, 11); ATT_SB();
;                   ATT_LDV(vc, 14); ATT_PV(va, 12); ATT_SB(); ATT_LDV(va, 15); ATT_PV(vb, 13); ATT_SB(); ATT_PV(vc, 14); ATT_SB(); ATT_PV(va, 15); ATT_SB();
.LBB0_900:
	v_sub_f32_e32 v115, v115, v226
	v_exp_f32_e32 v115, v115
	v_sub_f32_e32 v116, v116, v226
	v_exp_f32_e32 v116, v116
	v_sub_f32_e32 v117, v117, v226
	v_exp_f32_e32 v117, v117
	v_sub_f32_e32 v118, v118, v226
	v_exp_f32_e32 v118, v118
	v_sub_f32_e32 v119, v119, v226
	v_exp_f32_e32 v119, v119
	v_sub_f32_e32 v120, v120, v226
	v_add_f32_e32 v212, v116, v115
	v_exp_f32_e32 v120, v120
	v_sub_f32_e32 v121, v121, v226
	v_add_f32_e32 v212, v117, v212
	v_exp_f32_e32 v121, v121
	v_sub_f32_e32 v213, v225, v226
	v_add_f32_e32 v212, v118, v212
	v_exp_f32_e32 v213, v213
	v_sub_f32_e32 v225, v230, v226
	v_add_f32_e32 v212, v119, v212
	v_exp_f32_e32 v225, v225
	v_sub_f32_e32 v228, v231, v226
	v_add_f32_e32 v212, v120, v212
	v_exp_f32_e32 v228, v228
	v_sub_f32_e32 v230, v233, v226
	v_add_f32_e32 v212, v121, v212
	v_exp_f32_e32 v230, v230
	v_sub_f32_e32 v231, v234, v226
	v_add_f32_e32 v212, v213, v212
	v_exp_f32_e32 v231, v231
	v_sub_f32_e32 v229, v229, v226
	v_add_f32_e32 v212, v225, v212
	v_exp_f32_e32 v229, v229
	v_sub_f32_e32 v232, v232, v226
	v_add_f32_e32 v212, v228, v212
	v_exp_f32_e32 v232, v232
	v_sub_f32_e32 v233, v235, v226
	v_add_f32_e32 v212, v230, v212
	v_exp_f32_e32 v233, v233
	v_sub_f32_e32 v114, v114, v226
	v_add_f32_e32 v212, v231, v212
	v_exp_f32_e32 v234, v114
	v_add_f32_e32 v212, v229, v212
	v_add_f32_e32 v212, v232, v212
	v_add_f32_e32 v212, v233, v212
	v_cvt_pk_bf16_f32 v114, v115, v116
	v_cvt_pk_bf16_f32 v115, v117, v118
	v_cvt_pk_bf16_f32 v118, v225, v228
	v_add_f32_e32 v225, v234, v212
	v_fmac_f32_e32 v225, v227, v0
	v_cvt_pk_bf16_f32 v116, v119, v120
	v_cvt_pk_bf16_f32 v117, v121, v213
	v_cvt_pk_bf16_f32 v119, v230, v231
	v_cvt_pk_bf16_f32 v120, v229, v232
	v_cvt_pk_bf16_f32 v121, v233, v234
	s_waitcnt lgkmcnt(5)
	v_mfma_f32_16x16x32_bf16 v[62:65], v[134:137], v[114:117], v[62:65]
	v_add_u32_e32 v0, 0x19840, v162
	ds_read_b64_tr_b16 v[134:135], v0
	v_add_u32_e32 v0, 0x1ba40, v162
	ds_read_b64_tr_b16 v[136:137], v0
	v_add_u32_e32 v0, 0x1dc40, v162
	ds_read_b64_tr_b16 v[228:229], v0
	v_add_u32_e32 v0, 0x1fe40, v162
	ds_read_b64_tr_b16 v[230:231], v0
	s_waitcnt lgkmcnt(7)
	v_mfma_f32_16x16x32_bf16 v[62:65], v[126:129], v[118:121], v[62:65]
	s_waitcnt lgkmcnt(5)
	v_mfma_f32_16x16x32_bf16 v[58:61], v[130:133], v[114:117], v[58:61]
	v_add_u32_e32 v0, 0x19860, v162
	ds_read_b64_tr_b16 v[126:127], v0
	v_add_u32_e32 v0, 0x1ba60, v162
	ds_read_b64_tr_b16 v[128:129], v0
	v_add_u32_e32 v0, 0x1dc60, v162
	ds_read_b64_tr_b16 v[130:131], v0
	v_add_u32_e32 v0, 0x1fe60, v162
	ds_read_b64_tr_b16 v[132:133], v0
	s_waitcnt lgkmcnt(8)
	v_mfma_f32_16x16x32_bf16 v[58:61], v[122:125], v[118:121], v[58:61]
	s_waitcnt lgkmcnt(6)
	v_mfma_f32_16x16x32_bf16 v[54:57], v[134:137], v[114:117], v[54:57]
	v_add_u32_e32 v0, 0x19880, v162
	ds_read_b64_tr_b16 v[122:123], v0
	v_add_u32_e32 v0, 0x1ba80, v162
	ds_read_b64_tr_b16 v[124:125], v0
	v_add_u32_e32 v0, 0x1dc80, v162
	ds_read_b64_tr_b16 v[134:135], v0
	v_add_u32_e32 v0, 0x1fe80, v162
	ds_read_b64_tr_b16 v[136:137], v0
	s_waitcnt lgkmcnt(8)
	v_mfma_f32_16x16x32_bf16 v[54:57], v[228:231], v[118:121], v[54:57]
	s_waitcnt lgkmcnt(6)
	v_mfma_f32_16x16x32_bf16 v[50:53], v[126:129], v[114:117], v[50:53]
	v_add_u32_e32 v0, 0x198a0, v162
	ds_read_b64_tr_b16 v[126:127], v0
	v_add_u32_e32 v0, 0x1baa0, v162
	ds_read_b64_tr_b16 v[128:129], v0
	v_add_u32_e32 v0, 0x1dca0, v162
	ds_read_b64_tr_b16 v[228:229], v0
	v_add_u32_e32 v0, 0x1fea0, v162
	ds_read_b64_tr_b16 v[230:231], v0
	s_waitcnt lgkmcnt(8)
	v_mfma_f32_16x16x32_bf16 v[50:53], v[130:133], v[118:121], v[50:53]
	s_waitcnt lgkmcnt(6)
; #define ATT_LDV(dst_, mt_) do { _Pragma("unroll") for (int e = 0; e < 2; ++e) { const LAS unsigned char* vp = vb_ + e * 17408 + (mt_) * 32; \
;                     const s16x4 a0 = ds_tr16(vp), a1 = ds_tr16(vp + 8704); dst_[e] = (bf16x8){a0[0], a0[1], a0[2], a0[3], a1[0], a1[1], a1[2], a1[3]}; } } while (0)
; #define ATT_PV(src_, mt_) do { _Pragma("unroll") for (int e = 0; e < 2; ++e) O[mt_] = mfma16(src_[e], pf[e], O[mt_]); } while (0)
; #define ATT_SB() __builtin_amdgcn_sched_barrier(0)
; __device__ __forceinline__ void attn_phase(LAS unsigned char* lds, const bf16* PROJ, bf16* MIX, const float* lq1, const float* lk1, const float* lq2, const float* lk2,
;                                            const float* norm_g, float lambda_init, int G, int wave_s) {
;     ...
;                   ATT_LDV(vc, 2); ATT_PV(va, 0); ATT_SB(); ATT_LDV(va, 3); ATT_PV(vb, 1); ATT_SB(); ATT_LDV(vb, 4); ATT_PV(vc, 2); ATT_SB(); ATT_LDV(vc, 5); ATT_PV(va, 3); ATT_SB();
;                   ATT_LDV(va, 6); ATT_PV(vb, 4); ATT_SB(); ATT_LDV(vb, 7); ATT_PV(vc, 5); ATT_SB(); ATT_LDV(vc, 8); ATT_PV(va, 6); ATT_SB(); ATT_LDV(va, 9); ATT_PV(vb, 7); ATT_SB();
;                   ATT_LDV(vb, 10); ATT_PV(vc, 8); ATT_SB(); ATT_LDV(vc, 11); ATT_PV(va, 9); ATT_SB(); ATT_LDV(va, 12); ATT_PV(vb, 10); ATT_SB(); ATT_LDV(vb, 13); ATT_PV(vc, 11); ATT_SB();
;                   ATT_LDV(vc, 14); ATT_PV(va, 12); ATT_SB(); ATT_LDV(va, 15); ATT_PV(vb, 13); ATT_SB(); ATT_PV(vc, 14); ATT_SB(); ATT_PV(va, 15); ATT_SB();
;                   }
;                 __syncthreads();
;               }
;             }
	v_mfma_f32_16x16x32_bf16 v[46:49], v[122:125], v[114:117], v[46:49]
	v_add_u32_e32 v0, 0x198c0, v162
	ds_read_b64_tr_b16 v[122:123], v0
	v_add_u32_e32 v0, 0x1bac0, v162
	ds_read_b64_tr_b16 v[124:125], v0
	v_add_u32_e32 v0, 0x1dcc0, v162
	ds_read_b64_tr_b16 v[130:131], v0
	v_add_u32_e32 v0, 0x1fec0, v162
	ds_read_b64_tr_b16 v[132:133], v0
	s_waitcnt lgkmcnt(8)
	v_mfma_f32_16x16x32_bf16 v[46:49], v[134:137], v[118:121], v[46:49]
	s_waitcnt lgkmcnt(6)
	v_mfma_f32_16x16x32_bf16 v[42:45], v[126:129], v[114:117], v[42:45]
	v_add_u32_e32 v0, 0x198e0, v162
	ds_read_b64_tr_b16 v[126:127], v0
	v_add_u32_e32 v0, 0x1bae0, v162
	ds_read_b64_tr_b16 v[128:129], v0
	v_add_u32_e32 v0, 0x1dce0, v162
	ds_read_b64_tr_b16 v[134:135], v0
	v_add_u32_e32 v0, 0x1fee0, v162
	ds_read_b64_tr_b16 v[136:137], v0
	s_waitcnt lgkmcnt(8)
	v_mfma_f32_16x16x32_bf16 v[42:45], v[228:231], v[118:121], v[42:45]
	s_waitcnt lgkmcnt(6)
	v_mfma_f32_16x16x32_bf16 v[38:41], v[122:125], v[114:117], v[38:41]
	v_add_u32_e32 v0, 0x19900, v162
	ds_read_b64_tr_b16 v[122:123], v0
	ds_read_b64_tr_b16 v[124:125], v178
	ds_read_b64_tr_b16 v[228:229], v179
	ds_read_b64_tr_b16 v[230:231], v180
	s_waitcnt lgkmcnt(8)
	v_mfma_f32_16x16x32_bf16 v[38:41], v[130:133], v[118:121], v[38:41]
	s_waitcnt lgkmcnt(6)
	v_mfma_f32_16x16x32_bf16 v[34:37], v[126:129], v[114:117], v[34:37]
	ds_read_b64_tr_b16 v[126:127], v181
	ds_read_b64_tr_b16 v[128:129], v182
	ds_read_b64_tr_b16 v[130:131], v183
	ds_read_b64_tr_b16 v[132:133], v184
	s_waitcnt lgkmcnt(8)
	v_mfma_f32_16x16x32_bf16 v[34:37], v[134:137], v[118:121], v[34:37]
	s_waitcnt lgkmcnt(6)
	v_mfma_f32_16x16x32_bf16 v[30:33], v[122:125], v[114:117], v[30:33]
	ds_read_b64_tr_b16 v[122:123], v185
	ds_read_b64_tr_b16 v[124:125], v186
	ds_read_b64_tr_b16 v[134:135], v187
	ds_read_b64_tr_b16 v[136:137], v188
	s_waitcnt lgkmcnt(8)
	v_mfma_f32_16x16x32_bf16 v[30:33], v[228:231], v[118:121], v[30:33]
	s_waitcnt lgkmcnt(6)
	v_mfma_f32_16x16x32_bf16 v[26:29], v[126:129], v[114:117], v[26:29]
	ds_read_b64_tr_b16 v[126:127], v189
	ds_read_b64_tr_b16 v[128:129], v190
	ds_read_b64_tr_b16 v[228:229], v191
	ds_read_b64_tr_b16 v[230:231], v192
	s_waitcnt lgkmcnt(8)
	v_mfma_f32_16x16x32_bf16 v[26:29], v[130:133], v[118:121], v[26:29]
	s_waitcnt lgkmcnt(6)
	v_mfma_f32_16x16x32_bf16 v[22:25], v[122:125], v[114:117], v[22:25]
	ds_read_b64_tr_b16 v[122:123], v193
	ds_read_b64_tr_b16 v[124:125], v194
	ds_read_b64_tr_b16 v[130:131], v195
	ds_read_b64_tr_b16 v[132:133], v196
	s_waitcnt lgkmcnt(8)
	v_mfma_f32_16x16x32_bf16 v[22:25], v[134:137], v[118:121], v[22:25]
	s_waitcnt lgkmcnt(6)
	v_mfma_f32_16x16x32_bf16 v[14:17], v[126:129], v[114:117], v[14:17]
	ds_read_b64_tr_b16 v[126:127], v197
	ds_read_b64_tr_b16 v[128:129], v198
	ds_read_b64_tr_b16 v[134:135], v199
	ds_read_b64_tr_b16 v[136:137], v200
	s_waitcnt lgkmcnt(8)
	v_mfma_f32_16x16x32_bf16 v[14:17], v[228:231], v[118:121], v[14:17]
	s_waitcnt lgkmcnt(6)
	v_mfma_f32_16x16x32_bf16 v[18:21], v[122:125], v[114:117], v[18:21]
	ds_read_b64_tr_b16 v[122:123], v201
	ds_read_b64_tr_b16 v[124:125], v202
	ds_read_b64_tr_b16 v[228:229], v203
	ds_read_b64_tr_b16 v[230:231], v204
	s_waitcnt lgkmcnt(8)
	v_mfma_f32_16x16x32_bf16 v[18:21], v[130:133], v[118:121], v[18:21]
	s_waitcnt lgkmcnt(6)
	v_mfma_f32_16x16x32_bf16 v[10:13], v[126:129], v[114:117], v[10:13]
	ds_read_b64_tr_b16 v[126:127], v205
	ds_read_b64_tr_b16 v[128:129], v206
	ds_read_b64_tr_b16 v[130:131], v207
	ds_read_b64_tr_b16 v[132:133], v208
	s_waitcnt lgkmcnt(8)
	v_mfma_f32_16x16x32_bf16 v[10:13], v[134:137], v[118:121], v[10:13]
	s_waitcnt lgkmcnt(6)
	v_mfma_f32_16x16x32_bf16 v[6:9], v[122:125], v[114:117], v[6:9]
	s_waitcnt lgkmcnt(4)
	v_mfma_f32_16x16x32_bf16 v[6:9], v[228:231], v[118:121], v[6:9]
	s_waitcnt lgkmcnt(2)
	v_mfma_f32_16x16x32_bf16 v[2:5], v[126:129], v[114:117], v[2:5]
	s_waitcnt lgkmcnt(0)
	v_mfma_f32_16x16x32_bf16 v[2:5], v[130:133], v[118:121], v[2:5]
	s_barrier
	s_branch .LBB0_888
